# v27 + first LayerNorm phase: gamma/beta loads hoisted out of the token loop and the next token's rows prefetched (nt) into spare VGPRs
# speedup vs baseline: 1.0167x; 1.0100x over previous
.LBB0_519:
	s_or_b64 exec, exec, s[0:1]
	v_mov_b32_e32 v8, v160
	s_and_b64 vcc, exec, s[70:71]
	s_waitcnt lgkmcnt(0)
	s_barrier
	s_cbranch_vccz .LBB0_523
	v_mbcnt_hi_u32_b32 v0, -1, v186
	v_and_b32_e32 v1, 64, v0
	v_add_u32_e32 v1, 64, v1
	v_xor_b32_e32 v2, 1, v0
	v_cmp_lt_i32_e32 vcc, v2, v1
	s_ashr_i32 s47, s46, 31
	v_ashrrev_i32_e32 v9, 31, v8
	v_cndmask_b32_e32 v2, v0, v2, vcc
	v_lshlrev_b32_e32 v12, 2, v2
	v_xor_b32_e32 v2, 2, v0
	v_cmp_lt_i32_e32 vcc, v2, v1
	v_readlane_b32 s16, v234, 7
	s_lshl_b64 s[0:1], s[46:47], 10
	v_cndmask_b32_e32 v2, v0, v2, vcc
	v_lshlrev_b32_e32 v13, 2, v2
	v_xor_b32_e32 v2, 4, v0
	v_cmp_lt_i32_e32 vcc, v2, v1
	v_lshlrev_b64 v[6:7], 4, v[8:9]
	v_readlane_b32 s28, v234, 19
	v_cndmask_b32_e32 v2, v0, v2, vcc
	v_lshlrev_b32_e32 v14, 2, v2
	v_xor_b32_e32 v2, 8, v0
	v_cmp_lt_i32_e32 vcc, v2, v1
	v_readlane_b32 s29, v234, 20
	v_readlane_b32 s30, v234, 21
	v_cndmask_b32_e32 v2, v0, v2, vcc
	v_lshlrev_b32_e32 v15, 2, v2
	v_xor_b32_e32 v2, 16, v0
	v_cmp_lt_i32_e32 vcc, v2, v1
	v_readlane_b32 s31, v234, 22
	v_lshl_add_u64 v[4:5], v[8:9], 2, s[0:1]
	v_cndmask_b32_e32 v2, v0, v2, vcc
	v_lshlrev_b32_e32 v16, 2, v2
	v_xor_b32_e32 v2, 32, v0
	v_cmp_lt_i32_e32 vcc, v2, v1
	s_lshl_b64 s[0:1], s[46:47], 12
	s_ashr_i32 s81, s80, 31
	v_cndmask_b32_e32 v0, v0, v2, vcc
	v_lshlrev_b32_e32 v17, 2, v0
	v_lshl_add_u64 v[0:1], s[28:29], 0, v[6:7]
	v_lshl_add_u64 v[2:3], s[30:31], 0, v[6:7]
	v_lshl_add_u64 v[6:7], s[0:1], 0, v[6:7]
	s_lshl_b64 s[0:1], s[46:47], 11
	v_readlane_b32 s17, v234, 8
	s_lshl_b64 s[4:5], s[80:81], 10
	s_lshl_b64 s[6:7], s[80:81], 12
	v_lshl_add_u64 v[8:9], v[8:9], 3, s[0:1]
	s_lshl_b64 s[8:9], s[80:81], 11
	s_mov_b32 s10, 0x3fb504f3
	v_mov_b32_e32 v18, 0x3727c5ac
	s_mov_b32 s3, 0xf800000
	v_mov_b32_e32 v19, 0x260
	s_mov_b32 s11, 0x10400000
	s_mov_b32 s12, 0xc3e00000
	v_mov_b32_e32 v20, 0x43e00000
	s_mov_b32 s13, 0xe400000
	s_mov_b32 s14, s46
	v_readlane_b32 s18, v234, 9
	v_readlane_b32 s19, v234, 10
	v_readlane_b32 s20, v234, 11
	v_readlane_b32 s21, v234, 12
	v_readlane_b32 s22, v234, 13
	v_readlane_b32 s23, v234, 14
	v_readlane_b32 s24, v234, 15
	v_readlane_b32 s25, v234, 16
	v_readlane_b32 s26, v234, 17
	v_readlane_b32 s27, v234, 18
	global_load_dwordx4 v[64:67], v[0:1], off
	global_load_dwordx4 v[68:71], v[0:1], off offset:1024
	global_load_dwordx4 v[72:75], v[0:1], off offset:2048
	global_load_dwordx4 v[76:79], v[0:1], off offset:3072
	global_load_dwordx4 v[80:83], v[2:3], off
	global_load_dwordx4 v[84:87], v[2:3], off offset:1024
	global_load_dwordx4 v[88:91], v[2:3], off offset:2048
	global_load_dwordx4 v[92:95], v[2:3], off offset:3072
	s_add_u32 s98, s84, 0x14400000
	s_addc_u32 s99, s85, 0
	s_add_u32 s100, s84, 0x10400000
	s_addc_u32 s101, s85, 0
	v_lshl_add_u64 v[124:125], s[16:17], 0, v[6:7]
	v_lshl_add_u64 v[126:127], s[98:99], 0, v[8:9]
	global_load_dwordx4 v[100:103], v[124:125], off nt
	global_load_dwordx4 v[104:107], v[124:125], off offset:1024 nt
	global_load_dwordx4 v[108:111], v[124:125], off offset:2048 nt
	global_load_dwordx4 v[112:115], v[124:125], off offset:3072 nt
	global_load_dwordx2 v[116:117], v[126:127], off nt
	global_load_dwordx2 v[118:119], v[126:127], off offset:512 nt
	global_load_dwordx2 v[120:121], v[126:127], off offset:1024 nt
	global_load_dwordx2 v[122:123], v[126:127], off offset:1536 nt
	s_waitcnt vmcnt(0)
.LBB0_521:
	s_waitcnt vmcnt(8)
	v_lshl_add_u64 v[10:11], s[100:101], 0, v[6:7]
	s_add_i32 s14, s14, s80
	v_lshl_add_u64 v[6:7], v[6:7], 0, s[6:7]
	v_lshl_add_u64 v[8:9], v[8:9], 0, s[8:9]
	s_cmpk_lt_i32 s14, 0x4000
	v_lshlrev_b32_e32 v54, 16, v116
	v_and_b32_e32 v55, 0xffff0000, v116
	v_lshlrev_b32_e32 v48, 16, v117
	v_and_b32_e32 v49, 0xffff0000, v117
	v_lshlrev_b32_e32 v56, 16, v118
	v_and_b32_e32 v57, 0xffff0000, v118
	v_lshlrev_b32_e32 v50, 16, v119
	v_and_b32_e32 v51, 0xffff0000, v119
	v_lshlrev_b32_e32 v58, 16, v120
	v_and_b32_e32 v59, 0xffff0000, v120
	v_lshlrev_b32_e32 v52, 16, v121
	v_and_b32_e32 v53, 0xffff0000, v121
	v_lshlrev_b32_e32 v60, 16, v122
	v_and_b32_e32 v61, 0xffff0000, v122
	v_lshlrev_b32_e32 v46, 16, v123
	v_and_b32_e32 v47, 0xffff0000, v123
	v_pk_fma_f32 v[32:33], v[102:103], s[10:11], v[48:49] op_sel_hi:[1,0,1]
	v_pk_fma_f32 v[30:31], v[100:101], s[10:11], v[54:55] op_sel_hi:[1,0,1]
	v_pk_fma_f32 v[36:37], v[106:107], s[10:11], v[50:51] op_sel_hi:[1,0,1]
	v_pk_fma_f32 v[34:35], v[104:105], s[10:11], v[56:57] op_sel_hi:[1,0,1]
	v_pk_fma_f32 v[40:41], v[110:111], s[10:11], v[52:53] op_sel_hi:[1,0,1]
	v_pk_fma_f32 v[44:45], v[114:115], s[10:11], v[46:47] op_sel_hi:[1,0,1]
	v_pk_fma_f32 v[38:39], v[108:109], s[10:11], v[58:59] op_sel_hi:[1,0,1]
	v_pk_fma_f32 v[42:43], v[112:113], s[10:11], v[60:61] op_sel_hi:[1,0,1]
	s_cbranch_scc0 .Lln5_skip
	v_lshl_add_u64 v[124:125], s[16:17], 0, v[6:7]
	v_lshl_add_u64 v[126:127], s[98:99], 0, v[8:9]
	global_load_dwordx4 v[100:103], v[124:125], off nt
	global_load_dwordx4 v[104:107], v[124:125], off offset:1024 nt
	global_load_dwordx4 v[108:111], v[124:125], off offset:2048 nt
	global_load_dwordx4 v[112:115], v[124:125], off offset:3072 nt
	global_load_dwordx2 v[116:117], v[126:127], off nt
	global_load_dwordx2 v[118:119], v[126:127], off offset:512 nt
	global_load_dwordx2 v[120:121], v[126:127], off offset:1024 nt
	global_load_dwordx2 v[122:123], v[126:127], off offset:1536 nt
.Lln5_skip:
	v_pk_mov_b32 v[46:47], v[30:31], v[32:33] op_sel:[1,0]
	v_mov_b32_e32 v48, v30
	v_mov_b32_e32 v49, v33
	v_pk_mov_b32 v[50:51], v[34:35], v[36:37] op_sel:[1,0]
	v_mov_b32_e32 v52, v34
	v_mov_b32_e32 v53, v37
	v_pk_add_f32 v[46:47], v[46:47], v[48:49]
	v_pk_add_f32 v[48:49], v[50:51], v[52:53]
	v_add_f32_e32 v21, v46, v47
	v_pk_add_f32 v[46:47], v[48:49], v[48:49] op_sel:[0,1] op_sel_hi:[1,0]
	v_add_f32_e32 v54, v38, v39
	v_add_f32_e32 v56, v40, v41
	v_mov_b32_e32 v59, v42
	v_mov_b32_e32 v55, v44
	v_mov_b32_e32 v57, v45
	v_add_f32_e32 v58, 0, v21
	v_mov_b32_e32 v47, v43
	v_pk_add_f32 v[50:51], v[54:55], v[56:57]
	v_pk_add_f32 v[46:47], v[58:59], v[46:47]
	s_nop 0
	v_pk_add_f32 v[46:47], v[46:47], v[50:51]
	s_nop 0
	v_add_f32_e32 v21, v46, v47
	ds_bpermute_b32 v46, v12, v21
	s_waitcnt lgkmcnt(0)
	v_add_f32_e32 v21, v21, v46
	ds_bpermute_b32 v46, v13, v21
	s_waitcnt lgkmcnt(0)
	v_add_f32_e32 v21, v21, v46
	ds_bpermute_b32 v46, v14, v21
	s_waitcnt lgkmcnt(0)
	v_add_f32_e32 v21, v21, v46
	ds_bpermute_b32 v46, v15, v21
	s_waitcnt lgkmcnt(0)
	v_add_f32_e32 v21, v21, v46
	ds_bpermute_b32 v46, v16, v21
	s_waitcnt lgkmcnt(0)
	v_add_f32_e32 v21, v21, v46
	ds_bpermute_b32 v46, v17, v21
	s_waitcnt lgkmcnt(0)
	v_add_f32_e32 v21, v21, v46
	v_fmamk_f32 v31, v21, 0xba800000, v31
	v_fmac_f32_e32 v30, 0xba800000, v21
	v_fmamk_f32 v33, v21, 0xba800000, v33
	v_fmac_f32_e32 v32, 0xba800000, v21
	v_fmamk_f32 v35, v21, 0xba800000, v35
	v_fmac_f32_e32 v34, 0xba800000, v21
	v_fmamk_f32 v37, v21, 0xba800000, v37
	v_fmac_f32_e32 v36, 0xba800000, v21
	v_pk_mul_f32 v[46:47], v[32:33], v[32:33]
	v_pk_mul_f32 v[48:49], v[30:31], v[30:31]
	v_pk_mul_f32 v[50:51], v[36:37], v[36:37]
	v_pk_mul_f32 v[52:53], v[34:35], v[34:35]
	v_fmac_f32_e32 v38, 0xba800000, v21
	v_fmac_f32_e32 v40, 0xba800000, v21
	v_pk_mov_b32 v[58:59], v[48:49], v[46:47] op_sel:[1,0]
	v_mov_b32_e32 v49, v47
	v_pk_mov_b32 v[46:47], v[52:53], v[50:51] op_sel:[1,0]
	v_mov_b32_e32 v53, v51
	v_fmamk_f32 v39, v21, 0xba800000, v39
	v_fmamk_f32 v41, v21, 0xba800000, v41
	v_mul_f32_e32 v54, v38, v38
	v_mul_f32_e32 v56, v40, v40
	v_pk_add_f32 v[48:49], v[58:59], v[48:49]
	v_pk_add_f32 v[46:47], v[46:47], v[52:53]
	v_fmamk_f32 v45, v21, 0xba800000, v45
	v_fmac_f32_e32 v44, 0xba800000, v21
	v_fmamk_f32 v43, v21, 0xba800000, v43
	v_fmac_f32_e32 v42, 0xba800000, v21
	v_pk_fma_f32 v[50:51], v[38:39], v[38:39], v[54:55] op_sel_hi:[1,1,0]
	v_pk_fma_f32 v[54:55], v[40:41], v[40:41], v[56:57] op_sel_hi:[1,1,0]
	v_pk_add_f32 v[48:49], v[48:49], v[48:49] op_sel_hi:[0,1]
	v_pk_add_f32 v[46:47], v[46:47], v[46:47] op_sel_hi:[0,1]
	v_mul_f32_e32 v50, v42, v42
	v_mul_f32_e32 v54, v43, v43
	v_mul_f32_e32 v48, v44, v44
	v_mul_f32_e32 v46, v45, v45
	v_pk_add_f32 v[50:51], v[50:51], v[54:55]
	v_pk_add_f32 v[46:47], v[48:49], v[46:47]
	s_nop 0
	v_pk_add_f32 v[46:47], v[50:51], v[46:47]
	v_mov_b32_e32 v51, 0
	v_add_f32_e32 v21, v46, v47
	ds_bpermute_b32 v46, v12, v21
	s_waitcnt lgkmcnt(0)
	v_add_f32_e32 v21, v21, v46
	ds_bpermute_b32 v46, v13, v21
	s_waitcnt lgkmcnt(0)
	v_add_f32_e32 v21, v21, v46
	ds_bpermute_b32 v46, v14, v21
	s_waitcnt lgkmcnt(0)
	v_add_f32_e32 v21, v21, v46
	ds_bpermute_b32 v46, v15, v21
	s_waitcnt lgkmcnt(0)
	v_add_f32_e32 v21, v21, v46
	ds_bpermute_b32 v46, v16, v21
	s_waitcnt lgkmcnt(0)
	v_add_f32_e32 v21, v21, v46
	ds_bpermute_b32 v46, v17, v21
	s_waitcnt lgkmcnt(0)
	v_add_f32_e32 v21, v21, v46
	v_fmamk_f32 v21, v21, 0x3a800000, v18
	v_mul_f32_e32 v46, 0x4f800000, v21
	v_cmp_gt_f32_e32 vcc, s3, v21
	s_nop 1
	v_cndmask_b32_e32 v21, v21, v46, vcc
	v_sqrt_f32_e32 v46, v21
	s_nop 0
	v_add_u32_e32 v47, -1, v46
	v_add_u32_e32 v48, 1, v46
	v_fma_f32 v49, -v47, v46, v21
	v_fma_f32 v50, -v48, v46, v21
	v_cmp_ge_f32_e64 s[0:1], 0, v49
	s_nop 1
	v_cndmask_b32_e64 v46, v46, v47, s[0:1]
	v_cmp_lt_f32_e64 s[0:1], 0, v50
	s_nop 1
	v_cndmask_b32_e64 v46, v46, v48, s[0:1]
	v_mul_f32_e32 v47, 0x37800000, v46
	v_cndmask_b32_e32 v46, v46, v47, vcc
	v_cmp_class_f32_e32 vcc, v21, v19
	s_nop 1
	v_cndmask_b32_e32 v21, v46, v21, vcc
	v_div_scale_f32 v46, s[0:1], v21, v21, 1.0
	v_rcp_f32_e32 v48, v46
	v_div_scale_f32 v47, vcc, 1.0, v21, 1.0
	v_fma_f32 v49, -v46, v48, 1.0
	v_fmac_f32_e32 v48, v49, v48
	v_mul_f32_e32 v49, v47, v48
	v_fma_f32 v50, -v46, v49, v47
	v_fmac_f32_e32 v49, v50, v48
	v_fma_f32 v46, -v46, v49, v47
	v_div_fmas_f32 v46, v46, v48, v49
	v_div_fixup_f32 v46, v46, v21, 1.0
	v_pk_mul_f32 v[30:31], v[30:31], v[46:47] op_sel_hi:[1,0]
	v_pk_mul_f32 v[32:33], v[32:33], v[46:47] op_sel_hi:[1,0]
	v_pk_fma_f32 v[22:23], v[64:65], v[30:31], v[80:81]
	v_pk_fma_f32 v[24:25], v[66:67], v[32:33], v[82:83]
	global_store_dwordx4 v[10:11], v[22:25], off nt
	v_pk_mul_f32 v[34:35], v[34:35], v[46:47] op_sel_hi:[1,0]
	v_pk_mul_f32 v[36:37], v[36:37], v[46:47] op_sel_hi:[1,0]
	v_pk_mul_f32 v[38:39], v[38:39], v[46:47] op_sel_hi:[1,0]
	v_pk_mul_f32 v[40:41], v[40:41], v[46:47] op_sel_hi:[1,0]
	v_mov_b32_e32 v21, 0
	v_med3_f32 v22, v22, s12, v20
	v_med3_f32 v23, v23, s12, v20
	v_mov_b32_e32 v47, 0
	v_cvt_pk_fp8_f32 v21, v22, v23
	v_mov_b32_e32 v50, 0
	v_pk_mul_f32 v[42:43], v[42:43], v[46:47] op_sel_hi:[1,0]
	v_pk_mul_f32 v[44:45], v[44:45], v[46:47] op_sel_hi:[1,0]
	v_med3_f32 v24, v24, s12, v20
	v_med3_f32 v25, v25, s12, v20
	v_cvt_pk_fp8_f32 v21, v24, v25 op_sel:[0,0,1]
	v_lshl_add_u64 v[48:49], s[84:85], 0, v[4:5]
	v_add_co_u32_e32 v48, vcc, s13, v48
	v_lshl_add_u64 v[4:5], v[4:5], 0, s[4:5]
	s_nop 0
	v_addc_co_u32_e32 v49, vcc, 0, v49, vcc
	v_pk_fma_f32 v[28:29], v[70:71], v[36:37], v[86:87]
	v_pk_fma_f32 v[26:27], v[68:69], v[34:35], v[84:85]
	global_store_dwordx4 v[10:11], v[26:29], off offset:1024 nt
	v_med3_f32 v22, v26, s12, v20
	v_med3_f32 v23, v27, s12, v20
	v_cvt_pk_fp8_f32 v47, v22, v23
	v_med3_f32 v24, v28, s12, v20
	v_med3_f32 v25, v29, s12, v20
	v_cvt_pk_fp8_f32 v47, v24, v25 op_sel:[0,0,1]
	v_pk_fma_f32 v[32:33], v[74:75], v[40:41], v[90:91]
	v_pk_fma_f32 v[30:31], v[72:73], v[38:39], v[88:89]
	global_store_dwordx4 v[10:11], v[30:33], off offset:2048 nt
	v_med3_f32 v22, v30, s12, v20
	v_med3_f32 v23, v31, s12, v20
	v_cvt_pk_fp8_f32 v50, v22, v23
	v_med3_f32 v24, v32, s12, v20
	v_med3_f32 v25, v33, s12, v20
	v_cvt_pk_fp8_f32 v50, v24, v25 op_sel:[0,0,1]
	v_pk_fma_f32 v[22:23], v[76:77], v[42:43], v[92:93]
	s_nop 0
	v_med3_f32 v26, v22, s12, v20
	v_med3_f32 v27, v23, s12, v20
	v_cvt_pk_fp8_f32 v51, v26, v27
	v_pk_fma_f32 v[24:25], v[78:79], v[44:45], v[94:95]
	global_store_dwordx4 v[10:11], v[22:25], off offset:3072 nt
	v_med3_f32 v10, v24, s12, v20
	v_med3_f32 v11, v25, s12, v20
	v_cvt_pk_fp8_f32 v51, v10, v11 op_sel:[0,0,1]
	global_store_dword v[48:49], v21, off
	global_store_dword v[48:49], v47, off offset:256
	global_store_dword v[48:49], v50, off offset:512
	global_store_dword v[48:49], v51, off offset:768
	s_cbranch_scc1 .LBB0_521
	v_readlane_b32 s81, v234, 49

	.amdhsa_kernel _Z14fwd_megakernel4Ptrs
		.amdhsa_group_segment_fixed_size 0
		.amdhsa_private_segment_fixed_size 0
		.amdhsa_kernarg_size 392
		.amdhsa_user_sgpr_count 2
		.amdhsa_user_sgpr_dispatch_ptr 0
		.amdhsa_user_sgpr_queue_ptr 0
		.amdhsa_user_sgpr_kernarg_segment_ptr 1
		.amdhsa_user_sgpr_dispatch_id 0
		.amdhsa_user_sgpr_kernarg_preload_length 0
		.amdhsa_user_sgpr_kernarg_preload_offset 0
		.amdhsa_user_sgpr_private_segment_size 0
		.amdhsa_uses_dynamic_stack 0
		.amdhsa_enable_private_segment 0
		.amdhsa_system_sgpr_workgroup_id_x 1
		.amdhsa_system_sgpr_workgroup_id_y 0
		.amdhsa_system_sgpr_workgroup_id_z 0
		.amdhsa_system_sgpr_workgroup_info 0
		.amdhsa_system_vgpr_workitem_id 2
		.amdhsa_next_free_vgpr 240
		.amdhsa_next_free_sgpr 102
		.amdhsa_accum_offset 240
		.amdhsa_reserve_vcc 1
		.amdhsa_float_round_mode_32 0
		.amdhsa_float_round_mode_16_64 0
		.amdhsa_float_denorm_mode_32 3
		.amdhsa_float_denorm_mode_16_64 3
		.amdhsa_dx10_clamp 1
		.amdhsa_ieee_mode 1
		.amdhsa_fp16_overflow 0
		.amdhsa_tg_split 0
		.amdhsa_exception_fp_ieee_invalid_op 0
		.amdhsa_exception_fp_denorm_src 0
		.amdhsa_exception_fp_ieee_div_zero 0
		.amdhsa_exception_fp_ieee_overflow 0
		.amdhsa_exception_fp_ieee_underflow 0
		.amdhsa_exception_fp_ieee_inexact 0
		.amdhsa_exception_int_div_zero 0
	.end_amdhsa_kernel

.Lfunc_end0:
	.size	_Z14fwd_megakernel4Ptrs, .Lfunc_end0-_Z14fwd_megakernel4Ptrs
	.set _Z14fwd_megakernel4Ptrs.num_vgpr, 240
	.set _Z14fwd_megakernel4Ptrs.num_agpr, 0
	.set _Z14fwd_megakernel4Ptrs.numbered_sgpr, 102
	.set _Z14fwd_megakernel4Ptrs.num_named_barrier, 0
	.set _Z14fwd_megakernel4Ptrs.private_seg_size, 0
	.set _Z14fwd_megakernel4Ptrs.uses_vcc, 1
	.set _Z14fwd_megakernel4Ptrs.uses_flat_scratch, 0
	.set _Z14fwd_megakernel4Ptrs.has_dyn_sized_stack, 0
	.set _Z14fwd_megakernel4Ptrs.has_recursion, 0
	.set _Z14fwd_megakernel4Ptrs.has_indirect_call, 0

amdhsa.kernels:
  - .agpr_count:     0
    .args:
      - .offset:         0
        .size:           136
        .value_kind:     by_value
      - .offset:         136
        .size:           4
        .value_kind:     hidden_block_count_x
      - .offset:         140
        .size:           4
        .value_kind:     hidden_block_count_y
      - .offset:         144
        .size:           4
        .value_kind:     hidden_block_count_z
      - .offset:         148
        .size:           2
        .value_kind:     hidden_group_size_x
      - .offset:         150
        .size:           2
        .value_kind:     hidden_group_size_y
      - .offset:         152
        .size:           2
        .value_kind:     hidden_group_size_z
      - .offset:         154
        .size:           2
        .value_kind:     hidden_remainder_x
      - .offset:         156
        .size:           2
        .value_kind:     hidden_remainder_y
      - .offset:         158
        .size:           2
        .value_kind:     hidden_remainder_z
      - .offset:         176
        .size:           8
        .value_kind:     hidden_global_offset_x
      - .offset:         184
        .size:           8
        .value_kind:     hidden_global_offset_y
      - .offset:         192
        .size:           8
        .value_kind:     hidden_global_offset_z
      - .offset:         200
        .size:           2
        .value_kind:     hidden_grid_dims
      - .offset:         224
        .size:           8
        .value_kind:     hidden_multigrid_sync_arg
      - .offset:         256
        .size:           4
        .value_kind:     hidden_dynamic_lds_size
    .group_segment_fixed_size: 0
    .kernarg_segment_align: 8
    .kernarg_segment_size: 392
    .language:       OpenCL C
    .language_version:
      - 2
      - 0
    .max_flat_workgroup_size: 512
    .name:           _Z14fwd_megakernel4Ptrs
    .private_segment_fixed_size: 0
    .sgpr_count:     108
    .sgpr_spill_count: 58
    .symbol:         _Z14fwd_megakernel4Ptrs.kd
    .uniform_work_group_size: 1
    .uses_dynamic_stack: false
    .vgpr_count:     240
    .vgpr_spill_count: 0
    .wavefront_size: 64
